# attention W_uv up-projection tail: 64 fragment loads batched 32 at a time instead of load-wait-mfma chain (on top of EpiR epilogue batching)
# baseline (speedup 1.0000x reference)
; #define MFMA16(a, b, c) __builtin_amdgcn_mfma_f32_16x16x32_bf16((a), (b), (c), 0, 0, 0)
; DI unsigned pk2(float lo, float hi) { const f32x2 v = {lo, hi}; const bf16x2_t b = __builtin_convertvector(v, bf16x2_t); return __builtin_bit_cast(unsigned, b); }
; DI void attn_unit(const Params& p, const bf16_t* kv, int nkt, int nvalid_last, int qrow, int head, int pos, unsigned char* smem) {
;     ...
;     lsum += __shfl_xor(lsum, 16); lsum += __shfl_xor(lsum, 32); const float inv = 1.0f / lsum;
;     bf16x8 po[8];
; #pragma unroll
;     for (int ks = 0; ks < 8; ++ks) { u32x4 u; u.x = pk2(ot[2 * ks][0] * inv, ot[2 * ks][1] * inv); u.y = pk2(ot[2 * ks][2] * inv, ot[2 * ks][3] * inv); u.z = pk2(ot[2 * ks + 1][0] * inv, ot[2 * ks + 1][1] * inv); u.w = pk2(ot[2 * ks + 1][2] * inv, ot[2 * ks + 1][3] * inv);
;         po[ks] = __builtin_bit_cast(bf16x8, u); }
;     const bf16_t* wv = (const bf16_t*)(ws + WS_WUVT) + (size_t)head * 32768 + lane * 8;
;     bf16_t* op = MIX + (size_t)(qrow) * KOUT + 1024 + head * 128 + 4 * gq;
;     f32x4 acc[8];
; #pragma unroll
;     for (int vt = 0; vt < 8; ++vt) acc[vt] = (f32x4){0.f, 0.f, 0.f, 0.f};
; #pragma unroll
;     for (int ks = 0; ks < 8; ++ks)
; #pragma unroll
;         for (int vt = 0; vt < 8; ++vt) { const bf16x8 a = *(const bf16x8*)(wv + (vt * 8 + ks) * 512); acc[vt] = MFMA16(a, po[ks], acc[vt]); }
.LBB0_695:
	s_or_b64 exec, exec, s[0:1]
	ds_bpermute_b32 v0, v176, v182
	v_ashrrev_i32_e32 v155, 31, v154
	s_waitcnt vmcnt(4)
	v_and_b32_e32 v32, 63, v151
	s_waitcnt vmcnt(3)
	v_lshlrev_b64 v[36:37], 12, v[140:141]
	v_lshlrev_b32_e32 v140, 4, v32
	s_waitcnt lgkmcnt(0)
	v_add_f32_e32 v0, v182, v0
	ds_bpermute_b32 v1, v177, v0
	v_lshlrev_b32_e32 v38, 7, v154
	v_lshl_add_u64 v[36:37], s[10:11], 0, v[36:37]
	v_ashrrev_i32_e32 v39, 31, v38
	s_waitcnt vmcnt(0)
	v_lshl_add_u64 v[48:49], v[38:39], 1, v[36:37]
	s_waitcnt lgkmcnt(0)
	v_add_f32_e32 v0, v0, v1
	v_div_scale_f32 v1, s[0:1], v0, v0, 1.0
	v_rcp_f32_e32 v2, v1
	s_mov_b32 s0, 0xe000
	v_fma_f32 v3, -v1, v2, 1.0
	v_fmac_f32_e32 v2, v3, v2
	v_div_scale_f32 v3, vcc, 1.0, v0, 1.0
	v_mul_f32_e32 v4, v3, v2
	v_fma_f32 v5, -v1, v4, v3
	v_fmac_f32_e32 v4, v5, v2
	v_fma_f32 v1, -v1, v4, v3
	v_div_fmas_f32 v1, v1, v2, v4
	v_div_fixup_f32 v34, v1, v0, 1.0
	v_pk_mul_f32 v[0:1], v[60:61], v[34:35] op_sel_hi:[1,0]
	v_pk_mul_f32 v[2:3], v[118:119], v[34:35] op_sel_hi:[1,0]
	v_cvt_pk_bf16_f32 v28, v0, v1
	v_pk_mul_f32 v[0:1], v[62:63], v[34:35] op_sel_hi:[1,0]
	s_nop 0
	v_cvt_pk_bf16_f32 v29, v0, v1
	v_pk_mul_f32 v[0:1], v[64:65], v[34:35] op_sel_hi:[1,0]
	s_nop 0
	v_cvt_pk_bf16_f32 v30, v0, v1
	v_pk_mul_f32 v[0:1], v[66:67], v[34:35] op_sel_hi:[1,0]
	s_nop 0
	v_cvt_pk_bf16_f32 v31, v0, v1
	v_pk_mul_f32 v[0:1], v[68:69], v[34:35] op_sel_hi:[1,0]
	s_nop 0
	v_cvt_pk_bf16_f32 v24, v0, v1
	v_pk_mul_f32 v[0:1], v[70:71], v[34:35] op_sel_hi:[1,0]
	s_nop 0
	v_cvt_pk_bf16_f32 v25, v0, v1
	v_pk_mul_f32 v[0:1], v[72:73], v[34:35] op_sel_hi:[1,0]
	s_nop 0
	v_cvt_pk_bf16_f32 v26, v0, v1
	v_pk_mul_f32 v[0:1], v[74:75], v[34:35] op_sel_hi:[1,0]
	s_nop 0
	v_cvt_pk_bf16_f32 v27, v0, v1
	v_pk_mul_f32 v[0:1], v[76:77], v[34:35] op_sel_hi:[1,0]
	s_nop 0
	v_cvt_pk_bf16_f32 v20, v0, v1
	v_pk_mul_f32 v[0:1], v[78:79], v[34:35] op_sel_hi:[1,0]
	s_nop 0
	v_cvt_pk_bf16_f32 v21, v0, v1
	v_pk_mul_f32 v[0:1], v[80:81], v[34:35] op_sel_hi:[1,0]
	s_nop 0
	v_cvt_pk_bf16_f32 v22, v0, v1
	v_pk_mul_f32 v[0:1], v[82:83], v[34:35] op_sel_hi:[1,0]
	s_nop 0
	v_cvt_pk_bf16_f32 v23, v0, v1
	v_pk_mul_f32 v[0:1], v[84:85], v[34:35] op_sel_hi:[1,0]
	s_nop 0
	v_cvt_pk_bf16_f32 v16, v0, v1
	v_pk_mul_f32 v[0:1], v[86:87], v[34:35] op_sel_hi:[1,0]
	s_nop 0
	v_cvt_pk_bf16_f32 v17, v0, v1
	v_pk_mul_f32 v[0:1], v[88:89], v[34:35] op_sel_hi:[1,0]
	s_nop 0
	v_cvt_pk_bf16_f32 v18, v0, v1
	v_pk_mul_f32 v[0:1], v[90:91], v[34:35] op_sel_hi:[1,0]
	s_nop 0
	v_cvt_pk_bf16_f32 v19, v0, v1
	v_pk_mul_f32 v[0:1], v[92:93], v[34:35] op_sel_hi:[1,0]
	s_nop 0
	v_cvt_pk_bf16_f32 v12, v0, v1
	v_pk_mul_f32 v[0:1], v[94:95], v[34:35] op_sel_hi:[1,0]
	s_nop 0
	v_cvt_pk_bf16_f32 v13, v0, v1
	v_pk_mul_f32 v[0:1], v[96:97], v[34:35] op_sel_hi:[1,0]
	s_nop 0
	v_cvt_pk_bf16_f32 v14, v0, v1
	v_pk_mul_f32 v[0:1], v[98:99], v[34:35] op_sel_hi:[1,0]
	s_nop 0
	v_cvt_pk_bf16_f32 v15, v0, v1
	v_pk_mul_f32 v[0:1], v[100:101], v[34:35] op_sel_hi:[1,0]
	s_nop 0
	v_cvt_pk_bf16_f32 v8, v0, v1
	v_pk_mul_f32 v[0:1], v[102:103], v[34:35] op_sel_hi:[1,0]
	s_nop 0
	v_cvt_pk_bf16_f32 v9, v0, v1
	v_pk_mul_f32 v[0:1], v[108:109], v[34:35] op_sel_hi:[1,0]
	s_nop 0
	v_cvt_pk_bf16_f32 v10, v0, v1
	v_pk_mul_f32 v[0:1], v[110:111], v[34:35] op_sel_hi:[1,0]
	s_nop 0
	v_cvt_pk_bf16_f32 v11, v0, v1
	v_pk_mul_f32 v[0:1], v[104:105], v[34:35] op_sel_hi:[1,0]
	s_nop 0
	v_cvt_pk_bf16_f32 v4, v0, v1
	v_pk_mul_f32 v[0:1], v[106:107], v[34:35] op_sel_hi:[1,0]
	s_nop 0
	v_cvt_pk_bf16_f32 v5, v0, v1
	v_pk_mul_f32 v[0:1], v[112:113], v[34:35] op_sel_hi:[1,0]
	s_nop 0
	v_cvt_pk_bf16_f32 v6, v0, v1
	v_pk_mul_f32 v[0:1], v[114:115], v[34:35] op_sel_hi:[1,0]
	s_nop 0
	v_cvt_pk_bf16_f32 v7, v0, v1
	v_pk_mul_f32 v[0:1], v[116:117], v[34:35] op_sel_hi:[1,0]
	s_nop 0
	v_cvt_pk_bf16_f32 v0, v0, v1
	v_cvt_pk_bf16_f32 v1, v2, v3
	v_pk_mul_f32 v[2:3], v[120:121], v[34:35] op_sel_hi:[1,0]
	v_pk_mul_f32 v[34:35], v[122:123], v[34:35] op_sel_hi:[1,0]
	v_cvt_pk_bf16_f32 v2, v2, v3
	v_cvt_pk_bf16_f32 v3, v34, v35
	v_lshl_add_u32 v50, v154, 16, v140
	v_lshlrev_b32_e32 v140, 1, v145
	v_add_u32_e32 v50, 0x1000, v50
	v_add_u32_e32 v51, 0x2000, v50
	v_add_u32_e32 v52, 0x4000, v50
	v_add_u32_e32 v53, 0x6000, v50
	v_add_u32_e32 v54, 0x8000, v50
	v_add_u32_e32 v55, 0xa000, v50
	v_add_u32_e32 v56, 0xc000, v50
	v_add_u32_e32 v57, 0xe000, v50
	global_load_dwordx4 v[96:99], v50, s[16:17] offset:-4096
	global_load_dwordx4 v[100:103], v51, s[16:17] offset:-4096
	global_load_dwordx4 v[104:107], v52, s[16:17] offset:-4096
	global_load_dwordx4 v[108:111], v53, s[16:17] offset:-4096
	global_load_dwordx4 v[112:115], v54, s[16:17] offset:-4096
	global_load_dwordx4 v[116:119], v55, s[16:17] offset:-4096
	global_load_dwordx4 v[120:123], v56, s[16:17] offset:-4096
	global_load_dwordx4 v[124:127], v57, s[16:17] offset:-4096
	global_load_dwordx4 v[128:131], v50, s[16:17] offset:-3072
	global_load_dwordx4 v[132:135], v51, s[16:17] offset:-3072
	global_load_dwordx4 v[136:139], v52, s[16:17] offset:-3072
	global_load_dwordx4 v[156:159], v53, s[16:17] offset:-3072
	global_load_dwordx4 v[160:163], v54, s[16:17] offset:-3072
	global_load_dwordx4 v[164:167], v55, s[16:17] offset:-3072
	global_load_dwordx4 v[168:171], v56, s[16:17] offset:-3072
	global_load_dwordx4 v[172:175], v57, s[16:17] offset:-3072
	global_load_dwordx4 v[176:179], v50, s[16:17] offset:-2048
	global_load_dwordx4 v[180:183], v51, s[16:17] offset:-2048
	global_load_dwordx4 v[184:187], v52, s[16:17] offset:-2048
	global_load_dwordx4 v[188:191], v53, s[16:17] offset:-2048
	global_load_dwordx4 v[192:195], v54, s[16:17] offset:-2048
	global_load_dwordx4 v[196:199], v55, s[16:17] offset:-2048
	global_load_dwordx4 v[208:211], v56, s[16:17] offset:-2048
	global_load_dwordx4 v[212:215], v57, s[16:17] offset:-2048
	global_load_dwordx4 v[216:219], v50, s[16:17] offset:-1024
	global_load_dwordx4 v[220:223], v51, s[16:17] offset:-1024
	global_load_dwordx4 v[224:227], v52, s[16:17] offset:-1024
	global_load_dwordx4 v[228:231], v53, s[16:17] offset:-1024
	global_load_dwordx4 v[232:235], v54, s[16:17] offset:-1024
	global_load_dwordx4 v[236:239], v55, s[16:17] offset:-1024
	global_load_dwordx4 v[240:243], v56, s[16:17] offset:-1024
	global_load_dwordx4 v[244:247], v57, s[16:17] offset:-1024
	s_waitcnt vmcnt(24)
; #define MFMA16(a, b, c) __builtin_amdgcn_mfma_f32_16x16x32_bf16((a), (b), (c), 0, 0, 0)
; DI unsigned pk2(float lo, float hi) { const f32x2 v = {lo, hi}; const bf16x2_t b = __builtin_convertvector(v, bf16x2_t); return __builtin_bit_cast(unsigned, b); }
; DI void attn_unit(const Params& p, const bf16_t* kv, int nkt, int nvalid_last, int qrow, int head, int pos, unsigned char* smem) {
;     ...
;     for (int ks = 0; ks < 8; ++ks)
; #pragma unroll
;         for (int vt = 0; vt < 8; ++vt) { const bf16x8 a = *(const bf16x8*)(wv + (vt * 8 + ks) * 512); acc[vt] = MFMA16(a, po[ks], acc[vt]); }
; #pragma unroll
;     for (int vt = 0; vt < 8; ++vt) { u32x2 o; o.x = pk2(acc[vt][0], acc[vt][1]); o.y = pk2(acc[vt][2], acc[vt][3]); *(u32x2*)(op + 16 * vt) = o; }
	v_mfma_f32_16x16x32_bf16 v[64:67], v[96:99], v[28:31], 0
	v_mfma_f32_16x16x32_bf16 v[68:71], v[100:103], v[28:31], 0
	v_mfma_f32_16x16x32_bf16 v[72:75], v[104:107], v[28:31], 0
	v_mfma_f32_16x16x32_bf16 v[76:79], v[108:111], v[28:31], 0
	v_mfma_f32_16x16x32_bf16 v[80:83], v[112:115], v[28:31], 0
	v_mfma_f32_16x16x32_bf16 v[84:87], v[116:119], v[28:31], 0
	v_mfma_f32_16x16x32_bf16 v[88:91], v[120:123], v[28:31], 0
	v_mfma_f32_16x16x32_bf16 v[92:95], v[124:127], v[28:31], 0
	global_load_dwordx4 v[96:99], v50, s[16:17]
	global_load_dwordx4 v[100:103], v51, s[16:17]
	global_load_dwordx4 v[104:107], v52, s[16:17]
	global_load_dwordx4 v[108:111], v53, s[16:17]
	global_load_dwordx4 v[112:115], v54, s[16:17]
	global_load_dwordx4 v[116:119], v55, s[16:17]
	global_load_dwordx4 v[120:123], v56, s[16:17]
	global_load_dwordx4 v[124:127], v57, s[16:17]
	s_waitcnt vmcnt(24)
	v_mfma_f32_16x16x32_bf16 v[64:67], v[128:131], v[24:27], v[64:67]
	v_mfma_f32_16x16x32_bf16 v[68:71], v[132:135], v[24:27], v[68:71]
	v_mfma_f32_16x16x32_bf16 v[72:75], v[136:139], v[24:27], v[72:75]
	v_mfma_f32_16x16x32_bf16 v[76:79], v[156:159], v[24:27], v[76:79]
	v_mfma_f32_16x16x32_bf16 v[80:83], v[160:163], v[24:27], v[80:83]
	v_mfma_f32_16x16x32_bf16 v[84:87], v[164:167], v[24:27], v[84:87]
	v_mfma_f32_16x16x32_bf16 v[88:91], v[168:171], v[24:27], v[88:91]
	v_mfma_f32_16x16x32_bf16 v[92:95], v[172:175], v[24:27], v[92:95]
	global_load_dwordx4 v[128:131], v50, s[16:17] offset:1024
	global_load_dwordx4 v[132:135], v51, s[16:17] offset:1024
	global_load_dwordx4 v[136:139], v52, s[16:17] offset:1024
	global_load_dwordx4 v[156:159], v53, s[16:17] offset:1024
	global_load_dwordx4 v[160:163], v54, s[16:17] offset:1024
	global_load_dwordx4 v[164:167], v55, s[16:17] offset:1024
	global_load_dwordx4 v[168:171], v56, s[16:17] offset:1024
	global_load_dwordx4 v[172:175], v57, s[16:17] offset:1024
	s_waitcnt vmcnt(24)
	v_mfma_f32_16x16x32_bf16 v[64:67], v[176:179], v[20:23], v[64:67]
	v_mfma_f32_16x16x32_bf16 v[68:71], v[180:183], v[20:23], v[68:71]
	v_mfma_f32_16x16x32_bf16 v[72:75], v[184:187], v[20:23], v[72:75]
	v_mfma_f32_16x16x32_bf16 v[76:79], v[188:191], v[20:23], v[76:79]
	v_mfma_f32_16x16x32_bf16 v[80:83], v[192:195], v[20:23], v[80:83]
	v_mfma_f32_16x16x32_bf16 v[84:87], v[196:199], v[20:23], v[84:87]
	v_mfma_f32_16x16x32_bf16 v[88:91], v[208:211], v[20:23], v[88:91]
	v_mfma_f32_16x16x32_bf16 v[92:95], v[212:215], v[20:23], v[92:95]
	global_load_dwordx4 v[176:179], v50, s[16:17] offset:2048
	global_load_dwordx4 v[180:183], v51, s[16:17] offset:2048
	global_load_dwordx4 v[184:187], v52, s[16:17] offset:2048
	global_load_dwordx4 v[188:191], v53, s[16:17] offset:2048
	global_load_dwordx4 v[192:195], v54, s[16:17] offset:2048
	global_load_dwordx4 v[196:199], v55, s[16:17] offset:2048
	global_load_dwordx4 v[208:211], v56, s[16:17] offset:2048
	global_load_dwordx4 v[212:215], v57, s[16:17] offset:2048
	s_waitcnt vmcnt(24)
	v_mfma_f32_16x16x32_bf16 v[64:67], v[216:219], v[16:19], v[64:67]
	v_mfma_f32_16x16x32_bf16 v[68:71], v[220:223], v[16:19], v[68:71]
	v_mfma_f32_16x16x32_bf16 v[72:75], v[224:227], v[16:19], v[72:75]
	v_mfma_f32_16x16x32_bf16 v[76:79], v[228:231], v[16:19], v[76:79]
	v_mfma_f32_16x16x32_bf16 v[80:83], v[232:235], v[16:19], v[80:83]
	v_mfma_f32_16x16x32_bf16 v[84:87], v[236:239], v[16:19], v[84:87]
	v_mfma_f32_16x16x32_bf16 v[88:91], v[240:243], v[16:19], v[88:91]
	v_mfma_f32_16x16x32_bf16 v[92:95], v[244:247], v[16:19], v[92:95]
	global_load_dwordx4 v[216:219], v50, s[16:17] offset:3072
	global_load_dwordx4 v[220:223], v51, s[16:17] offset:3072
	global_load_dwordx4 v[224:227], v52, s[16:17] offset:3072
	global_load_dwordx4 v[228:231], v53, s[16:17] offset:3072
	global_load_dwordx4 v[232:235], v54, s[16:17] offset:3072
	global_load_dwordx4 v[236:239], v55, s[16:17] offset:3072
	global_load_dwordx4 v[240:243], v56, s[16:17] offset:3072
	global_load_dwordx4 v[244:247], v57, s[16:17] offset:3072
	s_waitcnt vmcnt(24)
	v_mfma_f32_16x16x32_bf16 v[64:67], v[96:99], v[12:15], v[64:67]
	v_mfma_f32_16x16x32_bf16 v[68:71], v[100:103], v[12:15], v[68:71]
	v_mfma_f32_16x16x32_bf16 v[72:75], v[104:107], v[12:15], v[72:75]
	v_mfma_f32_16x16x32_bf16 v[76:79], v[108:111], v[12:15], v[76:79]
	v_mfma_f32_16x16x32_bf16 v[80:83], v[112:115], v[12:15], v[80:83]
	v_mfma_f32_16x16x32_bf16 v[84:87], v[116:119], v[12:15], v[84:87]
	v_mfma_f32_16x16x32_bf16 v[88:91], v[120:123], v[12:15], v[88:91]
	v_mfma_f32_16x16x32_bf16 v[92:95], v[124:127], v[12:15], v[92:95]
	s_waitcnt vmcnt(16)
	v_mfma_f32_16x16x32_bf16 v[64:67], v[128:131], v[8:11], v[64:67]
	v_mfma_f32_16x16x32_bf16 v[68:71], v[132:135], v[8:11], v[68:71]
	v_mfma_f32_16x16x32_bf16 v[72:75], v[136:139], v[8:11], v[72:75]
	v_mfma_f32_16x16x32_bf16 v[76:79], v[156:159], v[8:11], v[76:79]
	v_mfma_f32_16x16x32_bf16 v[80:83], v[160:163], v[8:11], v[80:83]
	v_mfma_f32_16x16x32_bf16 v[84:87], v[164:167], v[8:11], v[84:87]
	v_mfma_f32_16x16x32_bf16 v[88:91], v[168:171], v[8:11], v[88:91]
	v_mfma_f32_16x16x32_bf16 v[92:95], v[172:175], v[8:11], v[92:95]
	s_waitcnt vmcnt(8)
	v_mfma_f32_16x16x32_bf16 v[64:67], v[176:179], v[4:7], v[64:67]
	v_mfma_f32_16x16x32_bf16 v[68:71], v[180:183], v[4:7], v[68:71]
	v_mfma_f32_16x16x32_bf16 v[72:75], v[184:187], v[4:7], v[72:75]
	v_mfma_f32_16x16x32_bf16 v[76:79], v[188:191], v[4:7], v[76:79]
	v_mfma_f32_16x16x32_bf16 v[80:83], v[192:195], v[4:7], v[80:83]
	v_mfma_f32_16x16x32_bf16 v[84:87], v[196:199], v[4:7], v[84:87]
	v_mfma_f32_16x16x32_bf16 v[88:91], v[208:211], v[4:7], v[88:91]
	v_mfma_f32_16x16x32_bf16 v[92:95], v[212:215], v[4:7], v[92:95]
	s_waitcnt vmcnt(0)
	v_mfma_f32_16x16x32_bf16 v[32:35], v[216:219], v[0:3], v[64:67]
	v_mfma_f32_16x16x32_bf16 v[4:7], v[220:223], v[0:3], v[68:71]
	v_mfma_f32_16x16x32_bf16 v[12:15], v[224:227], v[0:3], v[72:75]
	v_mfma_f32_16x16x32_bf16 v[8:11], v[228:231], v[0:3], v[76:79]
	v_mfma_f32_16x16x32_bf16 v[20:23], v[232:235], v[0:3], v[80:83]
	v_mfma_f32_16x16x32_bf16 v[16:19], v[236:239], v[0:3], v[84:87]
	v_mfma_f32_16x16x32_bf16 v[24:27], v[240:243], v[0:3], v[88:91]
	v_mfma_f32_16x16x32_bf16 v[0:3], v[244:247], v[0:3], v[92:95]
	v_lshl_add_u64 v[30:31], v[48:49], 0, v[140:141]
	v_lshl_add_u64 v[28:29], v[30:31], 0, s[88:89]
	s_nop 7
	v_cvt_pk_bf16_f32 v32, v32, v33
	v_cvt_pk_bf16_f32 v33, v34, v35
	global_store_dwordx2 v[28:29], v[32:33], off

; #define MFMA16(a, b, c) __builtin_amdgcn_mfma_f32_16x16x32_bf16((a), (b), (c), 0, 0, 0)
; DI unsigned pk2(float lo, float hi) { const f32x2 v = {lo, hi}; const bf16x2_t b = __builtin_convertvector(v, bf16x2_t); return __builtin_bit_cast(unsigned, b); }
; DI void attn_unit(const Params& p, const bf16_t* kv, int nkt, int nvalid_last, int qrow, int head, int pos, unsigned char* smem) {
;     ...
;         __syncthreads();
;     }
;     lsum += __shfl_xor(lsum, 16); lsum += __shfl_xor(lsum, 32); const float inv = 1.0f / lsum;
;     bf16x8 po[8];
; #pragma unroll
;     for (int ks = 0; ks < 8; ++ks) { u32x4 u; u.x = pk2(ot[2 * ks][0] * inv, ot[2 * ks][1] * inv); u.y = pk2(ot[2 * ks][2] * inv, ot[2 * ks][3] * inv); u.z = pk2(ot[2 * ks + 1][0] * inv, ot[2 * ks + 1][1] * inv); u.w = pk2(ot[2 * ks + 1][2] * inv, ot[2 * ks + 1][3] * inv);
;         po[ks] = __builtin_bit_cast(bf16x8, u); }
;     const bf16_t* wv = (const bf16_t*)(ws + WS_WUVT) + (size_t)head * 32768 + lane * 8;
;     bf16_t* op = MIX + (size_t)(qrow) * KOUT + 1024 + head * 128 + 4 * gq;
;     f32x4 acc[8];
; #pragma unroll
;     for (int vt = 0; vt < 8; ++vt) acc[vt] = (f32x4){0.f, 0.f, 0.f, 0.f};
; #pragma unroll
;     for (int ks = 0; ks < 8; ++ks)
; #pragma unroll
;         for (int vt = 0; vt < 8; ++vt) { const bf16x8 a = *(const bf16x8*)(wv + (vt * 8 + ks) * 512); acc[vt] = MFMA16(a, po[ks], acc[vt]); }
.LBB0_729:
	ds_bpermute_b32 v24, v153, v26
	v_lshlrev_b32_e32 v140, 4, v151
	s_waitcnt lgkmcnt(0)
	s_barrier
	v_add_f32_e32 v24, v26, v24
	ds_bpermute_b32 v25, v155, v24
	v_ashrrev_i32_e32 v155, 31, v154
	s_waitcnt lgkmcnt(0)
	v_add_f32_e32 v24, v24, v25
	v_div_scale_f32 v25, s[0:1], v24, v24, 1.0
	v_rcp_f32_e32 v26, v25
	s_mov_b32 s0, 0xe000
	v_fma_f32 v27, -v25, v26, 1.0
	v_fmac_f32_e32 v26, v27, v26
	v_div_scale_f32 v27, vcc, 1.0, v24, 1.0
	v_mul_f32_e32 v28, v27, v26
	v_fma_f32 v29, -v25, v28, v27
	v_fmac_f32_e32 v28, v29, v26
	v_fma_f32 v25, -v25, v28, v27
	v_div_fmas_f32 v25, v25, v26, v28
	v_div_fixup_f32 v72, v25, v24, 1.0
	v_pk_mul_f32 v[0:1], v[0:1], v[72:73] op_sel_hi:[1,0]
	v_pk_mul_f32 v[8:9], v[8:9], v[72:73] op_sel_hi:[1,0]
	v_cvt_pk_bf16_f32 v30, v0, v1
	v_pk_mul_f32 v[0:1], v[2:3], v[72:73] op_sel_hi:[1,0]
	v_cvt_pk_bf16_f32 v28, v8, v9
	v_cvt_pk_bf16_f32 v31, v0, v1
	v_pk_mul_f32 v[0:1], v[4:5], v[72:73] op_sel_hi:[1,0]
	v_pk_mul_f32 v[8:9], v[10:11], v[72:73] op_sel_hi:[1,0]
	v_cvt_pk_bf16_f32 v24, v0, v1
	v_pk_mul_f32 v[0:1], v[6:7], v[72:73] op_sel_hi:[1,0]
	v_cvt_pk_bf16_f32 v29, v8, v9
	v_cvt_pk_bf16_f32 v25, v0, v1
	v_pk_mul_f32 v[0:1], v[12:13], v[72:73] op_sel_hi:[1,0]
	v_pk_mul_f32 v[2:3], v[66:67], v[72:73] op_sel_hi:[1,0]
	v_cvt_pk_bf16_f32 v26, v0, v1
	v_pk_mul_f32 v[0:1], v[14:15], v[72:73] op_sel_hi:[1,0]
	s_nop 0
	v_cvt_pk_bf16_f32 v27, v0, v1
	v_pk_mul_f32 v[0:1], v[20:21], v[72:73] op_sel_hi:[1,0]
	s_nop 0
	v_cvt_pk_bf16_f32 v20, v0, v1
	v_pk_mul_f32 v[0:1], v[22:23], v[72:73] op_sel_hi:[1,0]
	s_nop 0
	v_cvt_pk_bf16_f32 v21, v0, v1
	v_pk_mul_f32 v[0:1], v[16:17], v[72:73] op_sel_hi:[1,0]
	s_nop 0
	v_cvt_pk_bf16_f32 v22, v0, v1
	v_pk_mul_f32 v[0:1], v[18:19], v[72:73] op_sel_hi:[1,0]
	s_nop 0
	v_cvt_pk_bf16_f32 v23, v0, v1
	v_pk_mul_f32 v[0:1], v[32:33], v[72:73] op_sel_hi:[1,0]
	v_pk_mul_f32 v[32:33], v[70:71], v[72:73] op_sel_hi:[1,0]
	v_cvt_pk_bf16_f32 v16, v0, v1
	v_pk_mul_f32 v[0:1], v[34:35], v[72:73] op_sel_hi:[1,0]
	v_lshlrev_b64 v[34:35], 12, v[156:157]
	v_cvt_pk_bf16_f32 v17, v0, v1
	v_pk_mul_f32 v[0:1], v[36:37], v[72:73] op_sel_hi:[1,0]
	v_lshlrev_b32_e32 v36, 7, v154
	v_cvt_pk_bf16_f32 v18, v0, v1
	v_pk_mul_f32 v[0:1], v[38:39], v[72:73] op_sel_hi:[1,0]
	v_lshl_add_u64 v[34:35], s[10:11], 0, v[34:35]
	v_cvt_pk_bf16_f32 v19, v0, v1
	v_pk_mul_f32 v[0:1], v[40:41], v[72:73] op_sel_hi:[1,0]
	v_ashrrev_i32_e32 v37, 31, v36
	v_cvt_pk_bf16_f32 v12, v0, v1
	v_pk_mul_f32 v[0:1], v[42:43], v[72:73] op_sel_hi:[1,0]
	s_nop 0
	v_cvt_pk_bf16_f32 v13, v0, v1
	v_pk_mul_f32 v[0:1], v[44:45], v[72:73] op_sel_hi:[1,0]
	s_nop 0
	v_cvt_pk_bf16_f32 v14, v0, v1
	v_pk_mul_f32 v[0:1], v[46:47], v[72:73] op_sel_hi:[1,0]
	s_nop 0
	v_cvt_pk_bf16_f32 v15, v0, v1
	v_pk_mul_f32 v[0:1], v[48:49], v[72:73] op_sel_hi:[1,0]
	v_lshl_add_u64 v[48:49], v[36:37], 1, v[34:35]
	v_cvt_pk_bf16_f32 v8, v0, v1
	v_pk_mul_f32 v[0:1], v[50:51], v[72:73] op_sel_hi:[1,0]
	s_nop 0
	v_cvt_pk_bf16_f32 v9, v0, v1
	v_pk_mul_f32 v[0:1], v[52:53], v[72:73] op_sel_hi:[1,0]
	s_nop 0
	v_cvt_pk_bf16_f32 v10, v0, v1
	v_pk_mul_f32 v[0:1], v[54:55], v[72:73] op_sel_hi:[1,0]
	s_nop 0
	v_cvt_pk_bf16_f32 v11, v0, v1
	v_pk_mul_f32 v[0:1], v[56:57], v[72:73] op_sel_hi:[1,0]
	s_nop 0
	v_cvt_pk_bf16_f32 v4, v0, v1
	v_pk_mul_f32 v[0:1], v[58:59], v[72:73] op_sel_hi:[1,0]
	s_nop 0
	v_cvt_pk_bf16_f32 v5, v0, v1
	v_pk_mul_f32 v[0:1], v[60:61], v[72:73] op_sel_hi:[1,0]
	s_nop 0
	v_cvt_pk_bf16_f32 v6, v0, v1
	v_pk_mul_f32 v[0:1], v[62:63], v[72:73] op_sel_hi:[1,0]
	s_nop 0
	v_cvt_pk_bf16_f32 v7, v0, v1
	v_pk_mul_f32 v[0:1], v[64:65], v[72:73] op_sel_hi:[1,0]
	s_nop 0
	v_cvt_pk_bf16_f32 v0, v0, v1
	v_cvt_pk_bf16_f32 v1, v2, v3
	v_pk_mul_f32 v[2:3], v[68:69], v[72:73] op_sel_hi:[1,0]
	s_nop 0
	v_cvt_pk_bf16_f32 v2, v2, v3
	v_cvt_pk_bf16_f32 v3, v32, v33
	v_lshl_add_u32 v50, v154, 16, v140
	v_lshlrev_b32_e32 v140, 1, v145
	v_add_u32_e32 v50, 0x1000, v50
	v_add_u32_e32 v51, 0x2000, v50
	v_add_u32_e32 v52, 0x4000, v50
	v_add_u32_e32 v53, 0x6000, v50
	v_add_u32_e32 v54, 0x8000, v50
	v_add_u32_e32 v55, 0xa000, v50
	v_add_u32_e32 v56, 0xc000, v50
	v_add_u32_e32 v57, 0xe000, v50
	global_load_dwordx4 v[96:99], v50, s[16:17] offset:-4096
	global_load_dwordx4 v[100:103], v51, s[16:17] offset:-4096
	global_load_dwordx4 v[104:107], v52, s[16:17] offset:-4096
	global_load_dwordx4 v[108:111], v53, s[16:17] offset:-4096
	global_load_dwordx4 v[112:115], v54, s[16:17] offset:-4096
	global_load_dwordx4 v[116:119], v55, s[16:17] offset:-4096
	global_load_dwordx4 v[120:123], v56, s[16:17] offset:-4096
	global_load_dwordx4 v[124:127], v57, s[16:17] offset:-4096
	global_load_dwordx4 v[128:131], v50, s[16:17] offset:-3072
	global_load_dwordx4 v[132:135], v51, s[16:17] offset:-3072
	global_load_dwordx4 v[136:139], v52, s[16:17] offset:-3072
	global_load_dwordx4 v[156:159], v53, s[16:17] offset:-3072
	global_load_dwordx4 v[160:163], v54, s[16:17] offset:-3072
	global_load_dwordx4 v[164:167], v55, s[16:17] offset:-3072
	global_load_dwordx4 v[168:171], v56, s[16:17] offset:-3072
	global_load_dwordx4 v[172:175], v57, s[16:17] offset:-3072
	global_load_dwordx4 v[176:179], v50, s[16:17] offset:-2048
	global_load_dwordx4 v[180:183], v51, s[16:17] offset:-2048
	global_load_dwordx4 v[184:187], v52, s[16:17] offset:-2048
	global_load_dwordx4 v[188:191], v53, s[16:17] offset:-2048
	global_load_dwordx4 v[192:195], v54, s[16:17] offset:-2048
	global_load_dwordx4 v[196:199], v55, s[16:17] offset:-2048
	global_load_dwordx4 v[208:211], v56, s[16:17] offset:-2048
	global_load_dwordx4 v[212:215], v57, s[16:17] offset:-2048
	global_load_dwordx4 v[216:219], v50, s[16:17] offset:-1024
	global_load_dwordx4 v[220:223], v51, s[16:17] offset:-1024
	global_load_dwordx4 v[224:227], v52, s[16:17] offset:-1024
	global_load_dwordx4 v[228:231], v53, s[16:17] offset:-1024
	global_load_dwordx4 v[232:235], v54, s[16:17] offset:-1024
	global_load_dwordx4 v[236:239], v55, s[16:17] offset:-1024
	global_load_dwordx4 v[240:243], v56, s[16:17] offset:-1024
	global_load_dwordx4 v[244:247], v57, s[16:17] offset:-1024
	s_waitcnt vmcnt(24)
; #define MFMA16(a, b, c) __builtin_amdgcn_mfma_f32_16x16x32_bf16((a), (b), (c), 0, 0, 0)
; DI unsigned pk2(float lo, float hi) { const f32x2 v = {lo, hi}; const bf16x2_t b = __builtin_convertvector(v, bf16x2_t); return __builtin_bit_cast(unsigned, b); }
; DI void attn_unit(const Params& p, const bf16_t* kv, int nkt, int nvalid_last, int qrow, int head, int pos, unsigned char* smem) {
;     ...
;     for (int ks = 0; ks < 8; ++ks)
; #pragma unroll
;         for (int vt = 0; vt < 8; ++vt) { const bf16x8 a = *(const bf16x8*)(wv + (vt * 8 + ks) * 512); acc[vt] = MFMA16(a, po[ks], acc[vt]); }
; #pragma unroll
;     for (int vt = 0; vt < 8; ++vt) { u32x2 o; o.x = pk2(acc[vt][0], acc[vt][1]); o.y = pk2(acc[vt][2], acc[vt][3]); *(u32x2*)(op + 16 * vt) = o; }
	v_mfma_f32_16x16x32_bf16 v[64:67], v[96:99], v[28:31], 0
	v_mfma_f32_16x16x32_bf16 v[68:71], v[100:103], v[28:31], 0
	v_mfma_f32_16x16x32_bf16 v[72:75], v[104:107], v[28:31], 0
	v_mfma_f32_16x16x32_bf16 v[76:79], v[108:111], v[28:31], 0
	v_mfma_f32_16x16x32_bf16 v[80:83], v[112:115], v[28:31], 0
	v_mfma_f32_16x16x32_bf16 v[84:87], v[116:119], v[28:31], 0
	v_mfma_f32_16x16x32_bf16 v[88:91], v[120:123], v[28:31], 0
	v_mfma_f32_16x16x32_bf16 v[92:95], v[124:127], v[28:31], 0
	global_load_dwordx4 v[96:99], v50, s[16:17]
	global_load_dwordx4 v[100:103], v51, s[16:17]
	global_load_dwordx4 v[104:107], v52, s[16:17]
	global_load_dwordx4 v[108:111], v53, s[16:17]
	global_load_dwordx4 v[112:115], v54, s[16:17]
	global_load_dwordx4 v[116:119], v55, s[16:17]
	global_load_dwordx4 v[120:123], v56, s[16:17]
	global_load_dwordx4 v[124:127], v57, s[16:17]
	s_waitcnt vmcnt(24)
	v_mfma_f32_16x16x32_bf16 v[64:67], v[128:131], v[24:27], v[64:67]
	v_mfma_f32_16x16x32_bf16 v[68:71], v[132:135], v[24:27], v[68:71]
	v_mfma_f32_16x16x32_bf16 v[72:75], v[136:139], v[24:27], v[72:75]
	v_mfma_f32_16x16x32_bf16 v[76:79], v[156:159], v[24:27], v[76:79]
	v_mfma_f32_16x16x32_bf16 v[80:83], v[160:163], v[24:27], v[80:83]
	v_mfma_f32_16x16x32_bf16 v[84:87], v[164:167], v[24:27], v[84:87]
	v_mfma_f32_16x16x32_bf16 v[88:91], v[168:171], v[24:27], v[88:91]
	v_mfma_f32_16x16x32_bf16 v[92:95], v[172:175], v[24:27], v[92:95]
	global_load_dwordx4 v[128:131], v50, s[16:17] offset:1024
	global_load_dwordx4 v[132:135], v51, s[16:17] offset:1024
	global_load_dwordx4 v[136:139], v52, s[16:17] offset:1024
	global_load_dwordx4 v[156:159], v53, s[16:17] offset:1024
	global_load_dwordx4 v[160:163], v54, s[16:17] offset:1024
	global_load_dwordx4 v[164:167], v55, s[16:17] offset:1024
	global_load_dwordx4 v[168:171], v56, s[16:17] offset:1024
	global_load_dwordx4 v[172:175], v57, s[16:17] offset:1024
	s_waitcnt vmcnt(24)
	v_mfma_f32_16x16x32_bf16 v[64:67], v[176:179], v[20:23], v[64:67]
	v_mfma_f32_16x16x32_bf16 v[68:71], v[180:183], v[20:23], v[68:71]
	v_mfma_f32_16x16x32_bf16 v[72:75], v[184:187], v[20:23], v[72:75]
	v_mfma_f32_16x16x32_bf16 v[76:79], v[188:191], v[20:23], v[76:79]
	v_mfma_f32_16x16x32_bf16 v[80:83], v[192:195], v[20:23], v[80:83]
	v_mfma_f32_16x16x32_bf16 v[84:87], v[196:199], v[20:23], v[84:87]
	v_mfma_f32_16x16x32_bf16 v[88:91], v[208:211], v[20:23], v[88:91]
	v_mfma_f32_16x16x32_bf16 v[92:95], v[212:215], v[20:23], v[92:95]
	global_load_dwordx4 v[176:179], v50, s[16:17] offset:2048
	global_load_dwordx4 v[180:183], v51, s[16:17] offset:2048
	global_load_dwordx4 v[184:187], v52, s[16:17] offset:2048
	global_load_dwordx4 v[188:191], v53, s[16:17] offset:2048
	global_load_dwordx4 v[192:195], v54, s[16:17] offset:2048
	global_load_dwordx4 v[196:199], v55, s[16:17] offset:2048
	global_load_dwordx4 v[208:211], v56, s[16:17] offset:2048
	global_load_dwordx4 v[212:215], v57, s[16:17] offset:2048
	s_waitcnt vmcnt(24)
	v_mfma_f32_16x16x32_bf16 v[64:67], v[216:219], v[16:19], v[64:67]
	v_mfma_f32_16x16x32_bf16 v[68:71], v[220:223], v[16:19], v[68:71]
	v_mfma_f32_16x16x32_bf16 v[72:75], v[224:227], v[16:19], v[72:75]
	v_mfma_f32_16x16x32_bf16 v[76:79], v[228:231], v[16:19], v[76:79]
	v_mfma_f32_16x16x32_bf16 v[80:83], v[232:235], v[16:19], v[80:83]
	v_mfma_f32_16x16x32_bf16 v[84:87], v[236:239], v[16:19], v[84:87]
	v_mfma_f32_16x16x32_bf16 v[88:91], v[240:243], v[16:19], v[88:91]
	v_mfma_f32_16x16x32_bf16 v[92:95], v[244:247], v[16:19], v[92:95]
	global_load_dwordx4 v[216:219], v50, s[16:17] offset:3072
	global_load_dwordx4 v[220:223], v51, s[16:17] offset:3072
	global_load_dwordx4 v[224:227], v52, s[16:17] offset:3072
	global_load_dwordx4 v[228:231], v53, s[16:17] offset:3072
	global_load_dwordx4 v[232:235], v54, s[16:17] offset:3072
	global_load_dwordx4 v[236:239], v55, s[16:17] offset:3072
	global_load_dwordx4 v[240:243], v56, s[16:17] offset:3072
	global_load_dwordx4 v[244:247], v57, s[16:17] offset:3072
	s_waitcnt vmcnt(24)
	v_mfma_f32_16x16x32_bf16 v[64:67], v[96:99], v[12:15], v[64:67]
	v_mfma_f32_16x16x32_bf16 v[68:71], v[100:103], v[12:15], v[68:71]
	v_mfma_f32_16x16x32_bf16 v[72:75], v[104:107], v[12:15], v[72:75]
	v_mfma_f32_16x16x32_bf16 v[76:79], v[108:111], v[12:15], v[76:79]
	v_mfma_f32_16x16x32_bf16 v[80:83], v[112:115], v[12:15], v[80:83]
	v_mfma_f32_16x16x32_bf16 v[84:87], v[116:119], v[12:15], v[84:87]
	v_mfma_f32_16x16x32_bf16 v[88:91], v[120:123], v[12:15], v[88:91]
	v_mfma_f32_16x16x32_bf16 v[92:95], v[124:127], v[12:15], v[92:95]
	s_waitcnt vmcnt(16)
	v_mfma_f32_16x16x32_bf16 v[64:67], v[128:131], v[8:11], v[64:67]
	v_mfma_f32_16x16x32_bf16 v[68:71], v[132:135], v[8:11], v[68:71]
	v_mfma_f32_16x16x32_bf16 v[72:75], v[136:139], v[8:11], v[72:75]
	v_mfma_f32_16x16x32_bf16 v[76:79], v[156:159], v[8:11], v[76:79]
	v_mfma_f32_16x16x32_bf16 v[80:83], v[160:163], v[8:11], v[80:83]
	v_mfma_f32_16x16x32_bf16 v[84:87], v[164:167], v[8:11], v[84:87]
	v_mfma_f32_16x16x32_bf16 v[88:91], v[168:171], v[8:11], v[88:91]
	v_mfma_f32_16x16x32_bf16 v[92:95], v[172:175], v[8:11], v[92:95]
	s_waitcnt vmcnt(8)
	v_mfma_f32_16x16x32_bf16 v[64:67], v[176:179], v[4:7], v[64:67]
	v_mfma_f32_16x16x32_bf16 v[68:71], v[180:183], v[4:7], v[68:71]
	v_mfma_f32_16x16x32_bf16 v[72:75], v[184:187], v[4:7], v[72:75]
	v_mfma_f32_16x16x32_bf16 v[76:79], v[188:191], v[4:7], v[76:79]
	v_mfma_f32_16x16x32_bf16 v[80:83], v[192:195], v[4:7], v[80:83]
	v_mfma_f32_16x16x32_bf16 v[84:87], v[196:199], v[4:7], v[84:87]
	v_mfma_f32_16x16x32_bf16 v[88:91], v[208:211], v[4:7], v[88:91]
	v_mfma_f32_16x16x32_bf16 v[92:95], v[212:215], v[4:7], v[92:95]
	s_waitcnt vmcnt(0)
	v_mfma_f32_16x16x32_bf16 v[32:35], v[216:219], v[0:3], v[64:67]
	v_mfma_f32_16x16x32_bf16 v[4:7], v[220:223], v[0:3], v[68:71]
	v_mfma_f32_16x16x32_bf16 v[12:15], v[224:227], v[0:3], v[72:75]
	v_mfma_f32_16x16x32_bf16 v[8:11], v[228:231], v[0:3], v[76:79]
	v_mfma_f32_16x16x32_bf16 v[20:23], v[232:235], v[0:3], v[80:83]
	v_mfma_f32_16x16x32_bf16 v[16:19], v[236:239], v[0:3], v[84:87]
	v_mfma_f32_16x16x32_bf16 v[24:27], v[240:243], v[0:3], v[88:91]
	v_mfma_f32_16x16x32_bf16 v[0:3], v[244:247], v[0:3], v[92:95]
	v_lshl_add_u64 v[30:31], v[48:49], 0, v[140:141]
	v_lshl_add_u64 v[28:29], v[30:31], 0, s[88:89]
	s_nop 7
	v_cvt_pk_bf16_f32 v32, v32, v33
	v_cvt_pk_bf16_f32 v33, v34, v35
	global_store_dwordx2 v[28:29], v[32:33], off
